# grid barrier: non-leader workgroups wait on the cross-XCD release generation directly (one atomic + one poll round trip less per barrier); otherwise v65
# baseline (speedup 1.0000x reference)
; __device__ __forceinline__ unsigned xb_ld(unsigned* p)              { return __hip_atomic_load(p, __ATOMIC_RELAXED, __HIP_MEMORY_SCOPE_AGENT); }
; __device__ __forceinline__ unsigned xb_add(unsigned* p, unsigned v) { return __hip_atomic_fetch_add(p, v, __ATOMIC_RELAXED, __HIP_MEMORY_SCOPE_AGENT); }
; #define XB_SPIN(cond, bar) do { unsigned _sp = 0; while (cond) { __builtin_amdgcn_s_sleep(1); \
;     if ((++_sp & 255u) == 0u) { if (xb_ld(&(bar)[XB_TMO])) break; if (_sp > XB_SPIN_CAP) { atomicAdd(&(bar)[XB_TMO], 1u); break; } } } } while (0)
; __device__ __forceinline__ void xcd_barrier(const XcdBarrier& b, bool is_t0) {
;     ...
;         __builtin_amdgcn_s_waitcnt(0);
;         unsigned nloc = b.st[0], nx = b.st[1];
;         if (nloc == 0u) { xcd_barrier_complete(bar, b.x, nloc, nx); b.st[0] = nloc; b.st[1] = nx; }
;         const unsigned old = xb_add(&bar[XB_XSUB(b.x)], 1u);
;         const unsigned gen = old / nloc;
;         if (old + 1u == (gen + 1u) * nloc) {
;             __builtin_amdgcn_fence(__ATOMIC_RELEASE, "agent");
;             asm volatile("s_waitcnt vmcnt(0)" ::: "memory");
;             const unsigned og = xb_add(&bar[XB_TOP], 1u);
;             const unsigned tg = og / nx;
;             if (og + 1u == (tg + 1u) * nx) xb_add(&bar[XB_TOPGEN], 1u);
;             else XB_SPIN(xb_ld(&bar[XB_TOPGEN]) == tg, bar);
;             __builtin_amdgcn_fence(__ATOMIC_ACQUIRE, "agent");
;             xb_add(&bar[XB_XGEN(b.x)], 1u);
;             asm volatile("s_waitcnt vmcnt(0)" ::: "memory");
;         } else {
;             XB_SPIN(xb_ld(&bar[XB_XGEN(b.x)]) == gen, bar);
.LBB0_180:
	s_or_b64 exec, exec, s[8:9]
	v_cvt_f32_u32_e32 v4, v2
	s_waitcnt vmcnt(0)
	v_readfirstlane_b32 s6, v3
	v_sub_u32_e32 v3, 0, v2
	v_rcp_iflag_f32_e32 v4, v4
	v_add_u32_e32 v5, s6, v1
	v_mul_f32_e32 v4, 0x4f7ffffe, v4
	v_cvt_u32_f32_e32 v4, v4
	v_mul_lo_u32 v1, v3, v4
	v_mul_hi_u32 v1, v4, v1
	v_add_u32_e32 v1, v4, v1
	v_mul_hi_u32 v1, v5, v1
	v_mul_lo_u32 v3, v1, v2
	v_sub_u32_e32 v3, v5, v3
	v_add_u32_e32 v4, 1, v1
	v_cmp_ge_u32_e32 vcc, v3, v2
	s_nop 1
	v_cndmask_b32_e32 v1, v1, v4, vcc
	v_sub_u32_e32 v4, v3, v2
	v_cndmask_b32_e32 v3, v3, v4, vcc
	v_add_u32_e32 v4, 1, v1
	v_cmp_ge_u32_e32 vcc, v3, v2
	v_add_u32_e32 v3, 1, v5
	s_nop 0
	v_cndmask_b32_e32 v1, v1, v4, vcc
	v_mul_lo_u32 v4, v2, v1
	v_add_u32_e32 v2, v4, v2
	v_cmp_ne_u32_e32 vcc, v3, v2
	s_and_saveexec_b64 s[6:7], vcc
	s_xor_b64 s[6:7], exec, s[6:7]
	s_cbranch_execz .LBB0_194
	s_waitcnt lgkmcnt(0)
	v_mov_b32_e32 v0, 0x3100
	global_load_dword v0, v0, s[50:51] offset:1024 sc1
	s_add_u32 s10, s50, 0x3500
	s_addc_u32 s11, s51, 0
	s_waitcnt vmcnt(0)
	v_cmp_eq_u32_e32 vcc, v0, v1
	s_and_saveexec_b64 s[8:9], vcc
	s_cbranch_execz .LBB0_193
	s_mov_b32 s31, 1
	s_mov_b64 s[12:13], 0
	s_branch .LBB0_184

; __device__ __forceinline__ unsigned xb_ld(unsigned* p)              { return __hip_atomic_load(p, __ATOMIC_RELAXED, __HIP_MEMORY_SCOPE_AGENT); }
; __device__ __forceinline__ unsigned xb_add(unsigned* p, unsigned v) { return __hip_atomic_fetch_add(p, v, __ATOMIC_RELAXED, __HIP_MEMORY_SCOPE_AGENT); }
; #define XB_SPIN(cond, bar) do { unsigned _sp = 0; while (cond) { __builtin_amdgcn_s_sleep(1); \
;     if ((++_sp & 255u) == 0u) { if (xb_ld(&(bar)[XB_TMO])) break; if (_sp > XB_SPIN_CAP) { atomicAdd(&(bar)[XB_TMO], 1u); break; } } } } while (0)
; __device__ __forceinline__ void xcd_barrier(const XcdBarrier& b, bool is_t0) {
;     ...
;         __builtin_amdgcn_s_waitcnt(0);
;         unsigned nloc = b.st[0], nx = b.st[1];
;         if (nloc == 0u) { xcd_barrier_complete(bar, b.x, nloc, nx); b.st[0] = nloc; b.st[1] = nx; }
;         const unsigned old = xb_add(&bar[XB_XSUB(b.x)], 1u);
;         const unsigned gen = old / nloc;
;         if (old + 1u == (gen + 1u) * nloc) {
;             __builtin_amdgcn_fence(__ATOMIC_RELEASE, "agent");
;             asm volatile("s_waitcnt vmcnt(0)" ::: "memory");
;             const unsigned og = xb_add(&bar[XB_TOP], 1u);
;             const unsigned tg = og / nx;
;             if (og + 1u == (tg + 1u) * nx) xb_add(&bar[XB_TOPGEN], 1u);
;             else XB_SPIN(xb_ld(&bar[XB_TOPGEN]) == tg, bar);
;             __builtin_amdgcn_fence(__ATOMIC_ACQUIRE, "agent");
;             xb_add(&bar[XB_XGEN(b.x)], 1u);
;             asm volatile("s_waitcnt vmcnt(0)" ::: "memory");
;         } else {
;             XB_SPIN(xb_ld(&bar[XB_XGEN(b.x)]) == gen, bar);
.LBB0_256:
	s_or_b64 exec, exec, s[8:9]
	v_cvt_f32_u32_e32 v4, v2
	s_waitcnt vmcnt(0)
	v_readfirstlane_b32 s6, v3
	v_sub_u32_e32 v3, 0, v2
	v_rcp_iflag_f32_e32 v4, v4
	v_add_u32_e32 v5, s6, v1
	v_mul_f32_e32 v4, 0x4f7ffffe, v4
	v_cvt_u32_f32_e32 v4, v4
	v_mul_lo_u32 v1, v3, v4
	v_mul_hi_u32 v1, v4, v1
	v_add_u32_e32 v1, v4, v1
	v_mul_hi_u32 v1, v5, v1
	v_mul_lo_u32 v3, v1, v2
	v_sub_u32_e32 v3, v5, v3
	v_add_u32_e32 v4, 1, v1
	v_cmp_ge_u32_e32 vcc, v3, v2
	s_nop 1
	v_cndmask_b32_e32 v1, v1, v4, vcc
	v_sub_u32_e32 v4, v3, v2
	v_cndmask_b32_e32 v3, v3, v4, vcc
	v_add_u32_e32 v4, 1, v1
	v_cmp_ge_u32_e32 vcc, v3, v2
	v_add_u32_e32 v3, 1, v5
	s_nop 0
	v_cndmask_b32_e32 v1, v1, v4, vcc
	v_mul_lo_u32 v4, v2, v1
	v_add_u32_e32 v2, v4, v2
	v_cmp_ne_u32_e32 vcc, v3, v2
	s_and_saveexec_b64 s[6:7], vcc
	s_xor_b64 s[6:7], exec, s[6:7]
	s_cbranch_execz .LBB0_270
	s_waitcnt lgkmcnt(0)
	v_mov_b32_e32 v0, 0x3100
	global_load_dword v0, v0, s[50:51] offset:1024 sc1
	s_add_u32 s10, s50, 0x3500
	s_addc_u32 s11, s51, 0
	s_waitcnt vmcnt(0)
	v_cmp_eq_u32_e32 vcc, v0, v1
	s_and_saveexec_b64 s[8:9], vcc
	s_cbranch_execz .LBB0_269
	s_mov_b32 s30, 1
	s_mov_b64 s[12:13], 0
	s_branch .LBB0_260

; __device__ __forceinline__ unsigned xb_ld(unsigned* p)              { return __hip_atomic_load(p, __ATOMIC_RELAXED, __HIP_MEMORY_SCOPE_AGENT); }
; __device__ __forceinline__ unsigned xb_add(unsigned* p, unsigned v) { return __hip_atomic_fetch_add(p, v, __ATOMIC_RELAXED, __HIP_MEMORY_SCOPE_AGENT); }
; #define XB_SPIN(cond, bar) do { unsigned _sp = 0; while (cond) { __builtin_amdgcn_s_sleep(1); \
;     if ((++_sp & 255u) == 0u) { if (xb_ld(&(bar)[XB_TMO])) break; if (_sp > XB_SPIN_CAP) { atomicAdd(&(bar)[XB_TMO], 1u); break; } } } } while (0)
; __device__ __forceinline__ void xcd_barrier(const XcdBarrier& b, bool is_t0) {
;     ...
;         __builtin_amdgcn_s_waitcnt(0);
;         unsigned nloc = b.st[0], nx = b.st[1];
;         if (nloc == 0u) { xcd_barrier_complete(bar, b.x, nloc, nx); b.st[0] = nloc; b.st[1] = nx; }
;         const unsigned old = xb_add(&bar[XB_XSUB(b.x)], 1u);
;         const unsigned gen = old / nloc;
;         if (old + 1u == (gen + 1u) * nloc) {
;             __builtin_amdgcn_fence(__ATOMIC_RELEASE, "agent");
;             asm volatile("s_waitcnt vmcnt(0)" ::: "memory");
;             const unsigned og = xb_add(&bar[XB_TOP], 1u);
;             const unsigned tg = og / nx;
;             if (og + 1u == (tg + 1u) * nx) xb_add(&bar[XB_TOPGEN], 1u);
;             else XB_SPIN(xb_ld(&bar[XB_TOPGEN]) == tg, bar);
;             __builtin_amdgcn_fence(__ATOMIC_ACQUIRE, "agent");
;             xb_add(&bar[XB_XGEN(b.x)], 1u);
;             asm volatile("s_waitcnt vmcnt(0)" ::: "memory");
;         } else {
;             XB_SPIN(xb_ld(&bar[XB_XGEN(b.x)]) == gen, bar);
.LBB0_864:
	s_or_b64 exec, exec, s[10:11]
	v_cvt_f32_u32_e32 v4, v2
	s_waitcnt vmcnt(0)
	v_readfirstlane_b32 s2, v3
	v_sub_u32_e32 v3, 0, v2
	v_rcp_iflag_f32_e32 v4, v4
	v_add_u32_e32 v5, s2, v1
	v_mul_f32_e32 v4, 0x4f7ffffe, v4
	v_cvt_u32_f32_e32 v4, v4
	v_mul_lo_u32 v1, v3, v4
	v_mul_hi_u32 v1, v4, v1
	v_add_u32_e32 v1, v4, v1
	v_mul_hi_u32 v1, v5, v1
	v_mul_lo_u32 v3, v1, v2
	v_sub_u32_e32 v3, v5, v3
	v_add_u32_e32 v4, 1, v1
	v_cmp_ge_u32_e32 vcc, v3, v2
	s_nop 1
	v_cndmask_b32_e32 v1, v1, v4, vcc
	v_sub_u32_e32 v4, v3, v2
	v_cndmask_b32_e32 v3, v3, v4, vcc
	v_add_u32_e32 v4, 1, v1
	v_cmp_ge_u32_e32 vcc, v3, v2
	v_add_u32_e32 v3, 1, v5
	s_nop 0
	v_cndmask_b32_e32 v1, v1, v4, vcc
	v_mul_lo_u32 v4, v2, v1
	v_add_u32_e32 v2, v4, v2
	v_cmp_ne_u32_e32 vcc, v3, v2
	s_and_saveexec_b64 s[2:3], vcc
	s_xor_b64 s[8:9], exec, s[2:3]
	s_cbranch_execz .LBB0_878
	s_waitcnt lgkmcnt(0)
	v_mov_b32_e32 v0, 0x3100
	global_load_dword v0, v0, s[50:51] offset:1024 sc1
	s_add_u32 s12, s50, 0x3500
	s_addc_u32 s13, s51, 0
	s_waitcnt vmcnt(0)
	v_cmp_eq_u32_e32 vcc, v0, v1
	s_and_saveexec_b64 s[10:11], vcc
	s_cbranch_execz .LBB0_877
	s_mov_b32 s31, 1
	s_mov_b64 s[14:15], 0
	s_branch .LBB0_868

; __device__ __forceinline__ unsigned xb_ld(unsigned* p)              { return __hip_atomic_load(p, __ATOMIC_RELAXED, __HIP_MEMORY_SCOPE_AGENT); }
; __device__ __forceinline__ unsigned xb_add(unsigned* p, unsigned v) { return __hip_atomic_fetch_add(p, v, __ATOMIC_RELAXED, __HIP_MEMORY_SCOPE_AGENT); }
; #define XB_SPIN(cond, bar) do { unsigned _sp = 0; while (cond) { __builtin_amdgcn_s_sleep(1); \
;     if ((++_sp & 255u) == 0u) { if (xb_ld(&(bar)[XB_TMO])) break; if (_sp > XB_SPIN_CAP) { atomicAdd(&(bar)[XB_TMO], 1u); break; } } } } while (0)
; __device__ __forceinline__ void xcd_barrier(const XcdBarrier& b, bool is_t0) {
;     ...
;         __builtin_amdgcn_s_waitcnt(0);
;         unsigned nloc = b.st[0], nx = b.st[1];
;         if (nloc == 0u) { xcd_barrier_complete(bar, b.x, nloc, nx); b.st[0] = nloc; b.st[1] = nx; }
;         const unsigned old = xb_add(&bar[XB_XSUB(b.x)], 1u);
;         const unsigned gen = old / nloc;
;         if (old + 1u == (gen + 1u) * nloc) {
;             __builtin_amdgcn_fence(__ATOMIC_RELEASE, "agent");
;             asm volatile("s_waitcnt vmcnt(0)" ::: "memory");
;             const unsigned og = xb_add(&bar[XB_TOP], 1u);
;             const unsigned tg = og / nx;
;             if (og + 1u == (tg + 1u) * nx) xb_add(&bar[XB_TOPGEN], 1u);
;             else XB_SPIN(xb_ld(&bar[XB_TOPGEN]) == tg, bar);
;             __builtin_amdgcn_fence(__ATOMIC_ACQUIRE, "agent");
;             xb_add(&bar[XB_XGEN(b.x)], 1u);
;             asm volatile("s_waitcnt vmcnt(0)" ::: "memory");
;         } else {
;             XB_SPIN(xb_ld(&bar[XB_XGEN(b.x)]) == gen, bar);
.LBB0_956:
	s_or_b64 exec, exec, s[10:11]
	v_cvt_f32_u32_e32 v4, v2
	s_waitcnt vmcnt(0)
	v_readfirstlane_b32 s2, v3
	v_sub_u32_e32 v3, 0, v2
	v_rcp_iflag_f32_e32 v4, v4
	v_add_u32_e32 v5, s2, v1
	v_mul_f32_e32 v4, 0x4f7ffffe, v4
	v_cvt_u32_f32_e32 v4, v4
	v_mul_lo_u32 v1, v3, v4
	v_mul_hi_u32 v1, v4, v1
	v_add_u32_e32 v1, v4, v1
	v_mul_hi_u32 v1, v5, v1
	v_mul_lo_u32 v3, v1, v2
	v_sub_u32_e32 v3, v5, v3
	v_add_u32_e32 v4, 1, v1
	v_cmp_ge_u32_e32 vcc, v3, v2
	s_nop 1
	v_cndmask_b32_e32 v1, v1, v4, vcc
	v_sub_u32_e32 v4, v3, v2
	v_cndmask_b32_e32 v3, v3, v4, vcc
	v_add_u32_e32 v4, 1, v1
	v_cmp_ge_u32_e32 vcc, v3, v2
	v_add_u32_e32 v3, 1, v5
	s_nop 0
	v_cndmask_b32_e32 v1, v1, v4, vcc
	v_mul_lo_u32 v4, v2, v1
	v_add_u32_e32 v2, v4, v2
	v_cmp_ne_u32_e32 vcc, v3, v2
	s_and_saveexec_b64 s[2:3], vcc
	s_xor_b64 s[8:9], exec, s[2:3]
	s_cbranch_execz .LBB0_970
	s_waitcnt lgkmcnt(0)
	v_mov_b32_e32 v0, 0x3100
	global_load_dword v0, v0, s[50:51] offset:1024 sc1
	s_add_u32 s12, s50, 0x3500
	s_addc_u32 s13, s51, 0
	s_waitcnt vmcnt(0)
	v_cmp_eq_u32_e32 vcc, v0, v1
	s_and_saveexec_b64 s[10:11], vcc
	s_cbranch_execz .LBB0_969
	s_mov_b32 s30, 1
	s_mov_b64 s[14:15], 0
	s_branch .LBB0_960

; __device__ __forceinline__ unsigned xb_ld(unsigned* p)              { return __hip_atomic_load(p, __ATOMIC_RELAXED, __HIP_MEMORY_SCOPE_AGENT); }
; __device__ __forceinline__ unsigned xb_add(unsigned* p, unsigned v) { return __hip_atomic_fetch_add(p, v, __ATOMIC_RELAXED, __HIP_MEMORY_SCOPE_AGENT); }
; #define XB_SPIN(cond, bar) do { unsigned _sp = 0; while (cond) { __builtin_amdgcn_s_sleep(1); \
;     if ((++_sp & 255u) == 0u) { if (xb_ld(&(bar)[XB_TMO])) break; if (_sp > XB_SPIN_CAP) { atomicAdd(&(bar)[XB_TMO], 1u); break; } } } } while (0)
; __device__ __forceinline__ void xcd_barrier(const XcdBarrier& b, bool is_t0) {
;     ...
;         __builtin_amdgcn_s_waitcnt(0);
;         unsigned nloc = b.st[0], nx = b.st[1];
;         if (nloc == 0u) { xcd_barrier_complete(bar, b.x, nloc, nx); b.st[0] = nloc; b.st[1] = nx; }
;         const unsigned old = xb_add(&bar[XB_XSUB(b.x)], 1u);
;         const unsigned gen = old / nloc;
;         if (old + 1u == (gen + 1u) * nloc) {
;             __builtin_amdgcn_fence(__ATOMIC_RELEASE, "agent");
;             asm volatile("s_waitcnt vmcnt(0)" ::: "memory");
;             const unsigned og = xb_add(&bar[XB_TOP], 1u);
;             const unsigned tg = og / nx;
;             if (og + 1u == (tg + 1u) * nx) xb_add(&bar[XB_TOPGEN], 1u);
;             else XB_SPIN(xb_ld(&bar[XB_TOPGEN]) == tg, bar);
;             __builtin_amdgcn_fence(__ATOMIC_ACQUIRE, "agent");
;             xb_add(&bar[XB_XGEN(b.x)], 1u);
;             asm volatile("s_waitcnt vmcnt(0)" ::: "memory");
;         } else {
;             XB_SPIN(xb_ld(&bar[XB_XGEN(b.x)]) == gen, bar);
.LBB0_1068:
	s_or_b64 exec, exec, s[6:7]
	v_cvt_f32_u32_e32 v4, v2
	s_waitcnt vmcnt(0)
	v_readfirstlane_b32 s4, v3
	v_sub_u32_e32 v3, 0, v2
	v_rcp_iflag_f32_e32 v4, v4
	v_add_u32_e32 v5, s4, v1
	v_mul_f32_e32 v4, 0x4f7ffffe, v4
	v_cvt_u32_f32_e32 v4, v4
	v_mul_lo_u32 v1, v3, v4
	v_mul_hi_u32 v1, v4, v1
	v_add_u32_e32 v1, v4, v1
	v_mul_hi_u32 v1, v5, v1
	v_mul_lo_u32 v3, v1, v2
	v_sub_u32_e32 v3, v5, v3
	v_add_u32_e32 v4, 1, v1
	v_cmp_ge_u32_e32 vcc, v3, v2
	s_nop 1
	v_cndmask_b32_e32 v1, v1, v4, vcc
	v_sub_u32_e32 v4, v3, v2
	v_cndmask_b32_e32 v3, v3, v4, vcc
	v_add_u32_e32 v4, 1, v1
	v_cmp_ge_u32_e32 vcc, v3, v2
	v_add_u32_e32 v3, 1, v5
	s_nop 0
	v_cndmask_b32_e32 v1, v1, v4, vcc
	v_mul_lo_u32 v4, v2, v1
	v_add_u32_e32 v2, v4, v2
	v_cmp_ne_u32_e32 vcc, v3, v2
	s_and_saveexec_b64 s[4:5], vcc
	s_xor_b64 s[4:5], exec, s[4:5]
	s_cbranch_execz .LBB0_1082
	s_waitcnt lgkmcnt(0)
	v_mov_b32_e32 v0, 0x3100
	global_load_dword v0, v0, s[50:51] offset:1024 sc1
	s_add_u32 s8, s50, 0x3500
	s_addc_u32 s9, s51, 0
	s_waitcnt vmcnt(0)
	v_cmp_eq_u32_e32 vcc, v0, v1
	s_and_saveexec_b64 s[6:7], vcc
	s_cbranch_execz .LBB0_1081
	s_mov_b32 s24, 1
	s_mov_b64 s[10:11], 0
	s_branch .LBB0_1072

; __device__ __forceinline__ unsigned xb_ld(unsigned* p)              { return __hip_atomic_load(p, __ATOMIC_RELAXED, __HIP_MEMORY_SCOPE_AGENT); }
; __device__ __forceinline__ unsigned xb_add(unsigned* p, unsigned v) { return __hip_atomic_fetch_add(p, v, __ATOMIC_RELAXED, __HIP_MEMORY_SCOPE_AGENT); }
; #define XB_SPIN(cond, bar) do { unsigned _sp = 0; while (cond) { __builtin_amdgcn_s_sleep(1); \
;     if ((++_sp & 255u) == 0u) { if (xb_ld(&(bar)[XB_TMO])) break; if (_sp > XB_SPIN_CAP) { atomicAdd(&(bar)[XB_TMO], 1u); break; } } } } while (0)
; __device__ __forceinline__ void xcd_barrier(const XcdBarrier& b, bool is_t0) {
;     ...
;         __builtin_amdgcn_s_waitcnt(0);
;         unsigned nloc = b.st[0], nx = b.st[1];
;         if (nloc == 0u) { xcd_barrier_complete(bar, b.x, nloc, nx); b.st[0] = nloc; b.st[1] = nx; }
;         const unsigned old = xb_add(&bar[XB_XSUB(b.x)], 1u);
;         const unsigned gen = old / nloc;
;         if (old + 1u == (gen + 1u) * nloc) {
;             __builtin_amdgcn_fence(__ATOMIC_RELEASE, "agent");
;             asm volatile("s_waitcnt vmcnt(0)" ::: "memory");
;             const unsigned og = xb_add(&bar[XB_TOP], 1u);
;             const unsigned tg = og / nx;
;             if (og + 1u == (tg + 1u) * nx) xb_add(&bar[XB_TOPGEN], 1u);
;             else XB_SPIN(xb_ld(&bar[XB_TOPGEN]) == tg, bar);
;             __builtin_amdgcn_fence(__ATOMIC_ACQUIRE, "agent");
;             xb_add(&bar[XB_XGEN(b.x)], 1u);
;             asm volatile("s_waitcnt vmcnt(0)" ::: "memory");
;         } else {
;             XB_SPIN(xb_ld(&bar[XB_XGEN(b.x)]) == gen, bar);
.LBB0_1141:
	s_or_b64 exec, exec, s[8:9]
	v_cvt_f32_u32_e32 v4, v2
	s_waitcnt vmcnt(0)
	v_readfirstlane_b32 s6, v3
	v_sub_u32_e32 v3, 0, v2
	v_rcp_iflag_f32_e32 v4, v4
	v_add_u32_e32 v5, s6, v1
	v_mul_f32_e32 v4, 0x4f7ffffe, v4
	v_cvt_u32_f32_e32 v4, v4
	v_mul_lo_u32 v1, v3, v4
	v_mul_hi_u32 v1, v4, v1
	v_add_u32_e32 v1, v4, v1
	v_mul_hi_u32 v1, v5, v1
	v_mul_lo_u32 v3, v1, v2
	v_sub_u32_e32 v3, v5, v3
	v_add_u32_e32 v4, 1, v1
	v_cmp_ge_u32_e32 vcc, v3, v2
	s_nop 1
	v_cndmask_b32_e32 v1, v1, v4, vcc
	v_sub_u32_e32 v4, v3, v2
	v_cndmask_b32_e32 v3, v3, v4, vcc
	v_add_u32_e32 v4, 1, v1
	v_cmp_ge_u32_e32 vcc, v3, v2
	v_add_u32_e32 v3, 1, v5
	s_nop 0
	v_cndmask_b32_e32 v1, v1, v4, vcc
	v_mul_lo_u32 v4, v2, v1
	v_add_u32_e32 v2, v4, v2
	v_cmp_ne_u32_e32 vcc, v3, v2
	s_and_saveexec_b64 s[6:7], vcc
	s_xor_b64 s[6:7], exec, s[6:7]
	s_cbranch_execz .LBB0_1155
	s_waitcnt lgkmcnt(0)
	v_mov_b32_e32 v0, 0x3100
	global_load_dword v0, v0, s[50:51] offset:1024 sc1
	s_add_u32 s10, s50, 0x3500
	s_addc_u32 s11, s51, 0
	s_waitcnt vmcnt(0)
	v_cmp_eq_u32_e32 vcc, v0, v1
	s_and_saveexec_b64 s[8:9], vcc
	s_cbranch_execz .LBB0_1154
	s_mov_b32 s29, 1
	s_mov_b64 s[12:13], 0
	s_branch .LBB0_1145
